# attention loop unrolled x2 with two K/V staging register sets: global loads for tile kt+2 stay in flight for two iterations, LDS store of tile kt+1 moved to the end of the iteration behind a counted v
# baseline (speedup 1.0000x reference)
; DI void attn_item(const int tid_, const Params& p, int l, int item, char* s0, char* s1, char* s2) {
;     ...
;   auto tile_info = [&](int kt, int& key0, int& nvalid) {
;     if (kmode == 0) { if (kt == 0) { key0 = 0; nvalid = 16; } else { key0 = 16 + 64 * (kt - 1); nvalid = 64; } }
;     else { key0 = 64 * kt; nvalid = (kt == 32) ? 16 : 64; }
;   };
;   auto gload = [&](int kt) {
;     int key0, nvalid;
;     tile_info(kt, key0, nvalid);
; #pragma unroll
;     for (int i = 0; i < 3; ++i) {
;       int idx = tid + 256 * i, row = idx / 12, ch = idx - row * 12;
;       const u16* src = (ch < 8) ? KN + (size_t)(key0 + row) * 512 + h * 64 + ch * 8 : KR + (size_t)(key0 + row) * 32 + (ch - 8) * 8;
;       kr[i] = (row < nvalid) ? *(const u32x4*)src : u32x4{0, 0, 0, 0};
;     }
; #pragma unroll
;     for (int i = 0; i < 2; ++i) {
;       int idx = tid + 256 * i, dv = idx >> 3, ch = idx & 7;
;       vr[i] = (ch * 8 < nvalid) ? *(const u32x4*)(VT + (size_t)dv * skv + key0 + ch * 8) : u32x4{0, 0, 0, 0};
;     }
;   };
;     ...
;   for (int kt = 0; kt < ntiles; ++kt) {
;     char* cur = (kt & 1) ? s1 : s0;
;     if (kt + 1 < ntiles) {
;       lstore(((kt + 1) & 1) ? s1 : s0);
;       if (kt + 2 < ntiles) gload(kt + 2);
.LatA_306:
	s_add_i32 s28, s48, -2
	s_bitcmp0_b32 s28, 0
	s_cselect_b64 s[30:31], -1, 0
	s_cmp_ge_i32 s48, s78
	s_cbranch_scc1 .LatA_319
	s_sub_i32 s50, s49, 48
	s_cmp_eq_u32 s48, 32
	s_cselect_b64 s[8:9], -1, 0
	s_and_b64 s[14:15], s[2:3], s[8:9]
	s_and_b64 s[8:9], s[2:3], exec
	s_cselect_b32 s8, s49, s50
	s_and_b64 s[14:15], s[14:15], exec
	v_mov_b32_e32 v194, v1
	v_mov_b32_e32 v195, v1
	s_cselect_b32 s50, 16, 64
	v_mov_b32_e32 v196, v1
	v_mov_b32_e32 v197, v1
	v_mov_b64_e32 v[190:191], v[194:195]
	v_cmp_gt_i32_e32 vcc, s50, v116
	v_mov_b64_e32 v[192:193], v[196:197]
	s_and_saveexec_b64 s[14:15], vcc
	v_add_u32_e32 v2, s8, v116
	v_ashrrev_i32_e32 v3, 31, v2
	v_lshlrev_b64 v[190:191], 10, v[2:3]
	v_lshlrev_b64 v[2:3], 6, v[2:3]
	v_lshl_add_u64 v[190:191], v[126:127], 0, v[190:191]
	v_lshl_add_u64 v[2:3], v[124:125], 0, v[2:3]
	v_cndmask_b32_e64 v3, v3, v191, s[42:43]
	v_cndmask_b32_e64 v2, v2, v190, s[42:43]
	flat_load_dwordx4 v[190:193], v[2:3]
.LatA_310:
	s_or_b64 exec, exec, s[14:15]
	v_cmp_gt_i32_e32 vcc, s50, v118
	s_and_saveexec_b64 s[14:15], vcc
	v_add_u32_e32 v2, s8, v118
	v_ashrrev_i32_e32 v3, 31, v2
	v_lshlrev_b64 v[194:195], 10, v[2:3]
	v_lshlrev_b64 v[2:3], 6, v[2:3]
	v_lshl_add_u64 v[194:195], v[130:131], 0, v[194:195]
	v_lshl_add_u64 v[2:3], v[128:129], 0, v[2:3]
	v_cndmask_b32_e64 v3, v3, v195, s[44:45]
	v_cndmask_b32_e64 v2, v2, v194, s[44:45]
	flat_load_dwordx4 v[194:197], v[2:3]
.LatA_312:
	s_or_b64 exec, exec, s[14:15]
	v_mov_b32_e32 v2, v1
	v_mov_b32_e32 v3, v1
	v_mov_b32_e32 v0, v1
	v_mov_b64_e32 v[200:201], v[2:3]
	v_cmp_gt_i32_e32 vcc, s50, v120
	v_mov_b64_e32 v[198:199], v[0:1]
	s_and_saveexec_b64 s[14:15], vcc
	v_add_u32_e32 v198, s8, v120
	v_ashrrev_i32_e32 v199, 31, v198
	v_lshlrev_b64 v[200:201], 10, v[198:199]
	v_lshlrev_b64 v[198:199], 6, v[198:199]
	v_lshl_add_u64 v[200:201], v[140:141], 0, v[200:201]
	v_lshl_add_u64 v[198:199], v[138:139], 0, v[198:199]
	v_cndmask_b32_e64 v199, v199, v201, s[46:47]
	v_cndmask_b32_e64 v198, v198, v200, s[46:47]
	flat_load_dwordx4 v[198:201], v[198:199]
.LatA_314:
	s_or_b64 exec, exec, s[14:15]
	v_mov_b64_e32 v[208:209], v[2:3]
	s_ashr_i32 s9, s8, 31
	v_cmp_gt_u32_e32 vcc, s50, v122
	v_mov_b64_e32 v[206:207], v[0:1]
	s_and_saveexec_b64 s[14:15], vcc
	v_lshl_add_u64 v[2:3], s[8:9], 1, v[142:143]
	flat_load_dwordx4 v[206:209], v[2:3]
.LatA_316:
	s_or_b64 exec, exec, s[14:15]
	v_mov_b32_e32 v2, v1
	v_mov_b32_e32 v3, v1
	v_mov_b32_e32 v0, v1
	v_mov_b64_e32 v[174:175], v[2:3]
	v_mov_b64_e32 v[172:173], v[0:1]
	s_and_saveexec_b64 s[14:15], vcc
	v_lshl_add_u64 v[2:3], s[8:9], 1, v[144:145]
	flat_load_dwordx4 v[172:175], v[2:3]

; DI void attn_item(const int tid_, const Params& p, int l, int item, char* s0, char* s1, char* s2) {
;     ...
;     if (kt < vis) {
;       int key0, nvalid;
;       tile_info(kt, key0, nvalid);
;       f32x4 s[4][2];
; #pragma unroll
;       for (int mt = 0; mt < 4; ++mt)
; #pragma unroll
;         for (int nt = 0; nt < 2; ++nt) s[mt][nt] = f32x4{0, 0, 0, 0};
; #pragma unroll
;       for (int ks = 0; ks < 3; ++ks)
; #pragma unroll
;         for (int mt = 0; mt < 4; ++mt) {
;           bf16x8 kf = *(const bf16x8*)(cur + (mt * 16 + c16) * 208 + ks * 64 + g * 16);
; #pragma unroll
;           for (int nt = 0; nt < 2; ++nt) s[mt][nt] = __builtin_amdgcn_mfma_f32_16x16x32_bf16(kf, qf[nt][ks], s[mt][nt], 0, 0, 0);
;         }
;       if (nvalid < 64) {
; #pragma unroll
;         for (int mt = 0; mt < 4; ++mt)
; #pragma unroll
;           for (int nt = 0; nt < 2; ++nt)
; #pragma unroll
;             for (int e = 0; e < 4; ++e)
;               if (mt * 16 + g * 4 + e >= nvalid) s[mt][nt][e] = -1e30f;
;       }
;     ...
;       const char* sV = cur + 64 * 208;
; #pragma unroll
;       for (int dt = 0; dt < 4; ++dt)
; #pragma unroll
;         for (int kk = 0; kk < 2; ++kk) {
;           u32x2 lo = *(const u32x2*)(sV + (dt * 16 + c16) * LDA + (kk * 32 + g * 4) * 2);
;           u32x2 hi = *(const u32x2*)(sV + (dt * 16 + c16) * LDA + (kk * 32 + 16 + g * 4) * 2);
;           u32x4 pk = u32x4{lo.x, lo.y, hi.x, hi.y};
.LatA_319:
	v_cmp_lt_u32_e32 vcc, s28, v150
	s_and_saveexec_b64 s[14:15], vcc
	s_cbranch_execz .LatA_305
	s_and_b64 s[8:9], s[30:31], exec
	s_cselect_b32 s28, 0, 0x6000
	v_or_b32_e32 v0, s28, v114
	v_add_u32_e32 v0, v0, v135
	s_waitcnt lgkmcnt(0)
	ds_read_b128 v[210:213], v0
	ds_read_b128 v[214:217], v0 offset:3328
	ds_read_b128 v[218:221], v0 offset:6656
	ds_read_b128 v[222:225], v0 offset:9984
	ds_read_b128 v[226:229], v0 offset:64
	ds_read_b128 v[230:233], v0 offset:3392
	ds_read_b128 v[234:237], v0 offset:6720
	ds_read_b128 v[238:241], v0 offset:10048
	ds_read_b128 v[242:245], v0 offset:128
	ds_read_b128 v[246:249], v0 offset:3456
	ds_read_b128 v[160:163], v0 offset:6784
	ds_read_b128 v[186:189], v0 offset:10112
	s_cmp_lg_u32 s48, 34
	s_cselect_b64 s[8:9], -1, 0
	s_xor_b64 s[50:51], s[2:3], -1
	s_or_b64 s[8:9], s[50:51], s[8:9]
	s_waitcnt lgkmcnt(8)
	v_mfma_f32_16x16x32_bf16 v[104:107], v[210:213], v[4:7], 0
	v_mfma_f32_16x16x32_bf16 v[88:91], v[210:213], v[16:19], 0
	v_mfma_f32_16x16x32_bf16 v[100:103], v[214:217], v[4:7], 0
	v_mfma_f32_16x16x32_bf16 v[84:87], v[214:217], v[16:19], 0
	v_mfma_f32_16x16x32_bf16 v[96:99], v[218:221], v[4:7], 0
	v_mfma_f32_16x16x32_bf16 v[80:83], v[218:221], v[16:19], 0
	v_mfma_f32_16x16x32_bf16 v[108:111], v[222:225], v[4:7], 0
	v_mfma_f32_16x16x32_bf16 v[92:95], v[222:225], v[16:19], 0
	s_waitcnt lgkmcnt(4)
	v_mfma_f32_16x16x32_bf16 v[104:107], v[226:229], v[8:11], v[104:107]
	v_mfma_f32_16x16x32_bf16 v[88:91], v[226:229], v[20:23], v[88:91]
	v_mfma_f32_16x16x32_bf16 v[100:103], v[230:233], v[8:11], v[100:103]
	v_mfma_f32_16x16x32_bf16 v[84:87], v[230:233], v[20:23], v[84:87]
	v_mfma_f32_16x16x32_bf16 v[96:99], v[234:237], v[8:11], v[96:99]
	v_mfma_f32_16x16x32_bf16 v[80:83], v[234:237], v[20:23], v[80:83]
	v_mfma_f32_16x16x32_bf16 v[108:111], v[238:241], v[8:11], v[108:111]
	v_mfma_f32_16x16x32_bf16 v[92:95], v[238:241], v[20:23], v[92:95]
	s_waitcnt lgkmcnt(0)
	v_mfma_f32_16x16x32_bf16 v[104:107], v[242:245], v[12:15], v[104:107]
	v_mfma_f32_16x16x32_bf16 v[88:91], v[242:245], v[24:27], v[88:91]
	v_mfma_f32_16x16x32_bf16 v[100:103], v[246:249], v[12:15], v[100:103]
	v_mfma_f32_16x16x32_bf16 v[84:87], v[246:249], v[24:27], v[84:87]
	v_mfma_f32_16x16x32_bf16 v[96:99], v[160:163], v[12:15], v[96:99]
	v_mfma_f32_16x16x32_bf16 v[80:83], v[160:163], v[24:27], v[80:83]
	v_mfma_f32_16x16x32_bf16 v[108:111], v[186:189], v[12:15], v[108:111]
	v_mfma_f32_16x16x32_bf16 v[92:95], v[186:189], v[24:27], v[92:95]
	s_and_b64 vcc, exec, s[8:9]
	s_and_b64 s[50:51], s[30:31], exec
	s_mov_b32 s50, 0x9400
	s_cselect_b32 s50, 0x3400, s50
	v_or_b32_e32 v186, s50, v157
	v_add_u32_e32 v186, v186, v158
	v_add_u32_e32 v187, 0x800, v186
	v_add_u32_e32 v188, 0x1000, v186
	v_add_u32_e32 v189, 0x1800, v186
	ds_read2_b64 v[210:213], v186 offset1:4
	ds_read2_b64 v[214:217], v186 offset0:8 offset1:12
	ds_read2_b64 v[218:221], v187 offset0:32 offset1:36
	ds_read2_b64 v[222:225], v187 offset0:40 offset1:44
	ds_read2_b64 v[226:229], v188 offset0:64 offset1:68
	ds_read2_b64 v[230:233], v188 offset0:72 offset1:76
	ds_read2_b64 v[234:237], v189 offset0:96 offset1:100
	ds_read2_b64 v[238:241], v189 offset0:104 offset1:108
	s_cbranch_vccnz .LatA_322
	s_nop 6
	v_mov_b32_e32 v92, 0xf149f2ca
	v_mov_b32_e32 v93, v92
	v_mov_b32_e32 v94, v92
	v_mov_b32_e32 v95, v92
	v_mov_b32_e32 v108, v92
	v_mov_b32_e32 v109, v92
	v_mov_b32_e32 v110, v92
	v_mov_b32_e32 v111, v92
	v_mov_b32_e32 v80, v92
	v_mov_b32_e32 v81, v92
	v_mov_b32_e32 v82, v92
	v_mov_b32_e32 v83, v92
	v_mov_b32_e32 v96, v92
	v_mov_b32_e32 v97, v92
	v_mov_b32_e32 v98, v92
	v_mov_b32_e32 v99, v92
	v_mov_b32_e32 v84, v92
	v_mov_b32_e32 v85, v92
	v_mov_b32_e32 v86, v92
	v_mov_b32_e32 v87, v92
	v_mov_b32_e32 v100, v92
	v_mov_b32_e32 v101, v92
	v_mov_b32_e32 v102, v92
	v_mov_b32_e32 v103, v92

; DI u32x2 pack4(f32x4 v) { return u32x2{pack2(v[0], v[1]), pack2(v[2], v[3])}; }
; DI float xmax16(float x) { u32x2 r = __builtin_amdgcn_permlane16_swap(__float_as_uint(x), __float_as_uint(x), false, false); return fmaxf(__uint_as_float(r.x), __uint_as_float(r.y)); }
; DI void attn_item(const int tid_, const Params& p, int l, int item, char* s0, char* s1, char* s2) {
;     ...
;       bf16x8 pf[2][2];
; #pragma unroll
;       for (int nt = 0; nt < 2; ++nt) {
;         float mx = -1e30f;
; #pragma unroll
;         for (int mt = 0; mt < 4; ++mt)
; #pragma unroll
;           for (int e = 0; e < 4; ++e) mx = fmaxf(mx, s[mt][nt][e]);
;         mx = xmax16(mx);
;         mx = xmax32(mx);
;         const float mnew = fmaxf(mrow[nt], mx);
;         const float alpha = __builtin_amdgcn_exp2f(mrow[nt] - mnew);
;         mrow[nt] = mnew;
;         float ps = 0.f;
; #pragma unroll
;         for (int mt = 0; mt < 4; ++mt)
; #pragma unroll
;           for (int e = 0; e < 4; ++e) {
;             float pv = __builtin_amdgcn_exp2f(s[mt][nt][e] - mnew);
;             s[mt][nt][e] = pv;
;             ps += pv;
;           }
;         lsum[nt] = lsum[nt] * alpha + ps;
;         if (__builtin_amdgcn_ballot_w64(alpha != 1.f) != 0ull) {
; #pragma unroll
;           for (int dt = 0; dt < 4; ++dt) o[dt][nt] *= alpha;
;         }
; #pragma unroll
;         for (int kk = 0; kk < 2; ++kk) {
;           u32x2 lo = pack4(s[2 * kk][nt]), hi = pack4(s[2 * kk + 1][nt]);
;           u32x4 pk = u32x4{lo.x, lo.y, hi.x, hi.y};
;           pf[nt][kk] = __builtin_bit_cast(bf16x8, pk);
;         }
;       }
;       const char* sV = cur + 64 * 208;
; #pragma unroll
;       for (int dt = 0; dt < 4; ++dt)
; #pragma unroll
;         for (int kk = 0; kk < 2; ++kk) {
;           u32x2 lo = *(const u32x2*)(sV + (dt * 16 + c16) * LDA + (kk * 32 + g * 4) * 2);
;           u32x2 hi = *(const u32x2*)(sV + (dt * 16 + c16) * LDA + (kk * 32 + 16 + g * 4) * 2);
;           u32x4 pk = u32x4{lo.x, lo.y, hi.x, hi.y};
;           bf16x8 vf = __builtin_bit_cast(bf16x8, pk);
; #pragma unroll
;           for (int nt = 0; nt < 2; ++nt) o[dt][nt] = __builtin_amdgcn_mfma_f32_16x16x32_bf16(vf, pf[nt][kk], o[dt][nt], 0, 0, 0);
;         }
;     }
;     __syncthreads();
;   }
.LatA_324:
	v_max3_f32 v0, v88, s8, v89
	v_max3_f32 v0, v0, v90, v91
	v_max3_f32 v0, v0, v84, v85
	v_max3_f32 v0, v0, v86, v87
	v_max3_f32 v0, v0, v80, v81
	v_max3_f32 v0, v0, v82, v83
	v_max3_f32 v0, v0, v92, v93
	v_max3_f32 v0, v0, v94, v95
	v_mov_b32_e32 v3, v0
	s_nop 1
	v_permlane16_swap_b32_e32 v0, v3
	v_max_f32_e32 v3, v3, v3
	v_max_f32_e32 v0, v0, v0
	v_max_f32_e32 v0, v0, v3
	v_mov_b32_e32 v3, v0
	s_nop 1
	v_permlane32_swap_b32_e32 v0, v3
	v_max3_f32 v3, v149, v0, v3
	v_sub_f32_e32 v0, v149, v3
	v_exp_f32_e32 v0, v0
	s_nop 0
	v_cmp_neq_f32_e32 vcc, 1.0, v0
	s_cbranch_vccz .LatA_304
	v_pk_mul_f32 v[54:55], v[54:55], v[0:1] op_sel_hi:[1,0]
	v_pk_mul_f32 v[52:53], v[52:53], v[0:1] op_sel_hi:[1,0]
	v_pk_mul_f32 v[46:47], v[46:47], v[0:1] op_sel_hi:[1,0]
	v_pk_mul_f32 v[44:45], v[44:45], v[0:1] op_sel_hi:[1,0]
	v_pk_mul_f32 v[34:35], v[34:35], v[0:1] op_sel_hi:[1,0]
	v_pk_mul_f32 v[32:33], v[32:33], v[0:1] op_sel_hi:[1,0]
	v_pk_mul_f32 v[38:39], v[38:39], v[0:1] op_sel_hi:[1,0]
	v_pk_mul_f32 v[36:37], v[36:37], v[0:1] op_sel_hi:[1,0]
	s_branch .LatA_304
.LatA_304:
	v_sub_f32_e32 v104, v104, v2
	v_exp_f32_e32 v149, v104
	v_sub_f32_e32 v105, v105, v2
	v_exp_f32_e32 v105, v105
	v_sub_f32_e32 v106, v106, v2
	v_exp_f32_e32 v106, v106
	v_sub_f32_e32 v107, v107, v2
	v_exp_f32_e32 v107, v107
	v_sub_f32_e32 v100, v100, v2
	v_add_f32_e32 v104, 0, v149
	v_exp_f32_e32 v159, v100
	v_sub_f32_e32 v101, v101, v2
	v_add_f32_e32 v104, v105, v104
	v_exp_f32_e32 v160, v101
	v_sub_f32_e32 v101, v102, v2
	v_add_f32_e32 v104, v106, v104
	v_exp_f32_e32 v161, v101
	v_sub_f32_e32 v101, v103, v2
	v_add_f32_e32 v104, v107, v104
	v_exp_f32_e32 v103, v101
	v_sub_f32_e32 v96, v96, v2
	v_add_f32_e32 v100, v159, v104
	v_exp_f32_e32 v96, v96
	v_sub_f32_e32 v97, v97, v2
	v_add_f32_e32 v100, v160, v100
	v_exp_f32_e32 v97, v97
	v_sub_f32_e32 v98, v98, v2
	v_add_f32_e32 v100, v161, v100
	v_exp_f32_e32 v98, v98
	v_sub_f32_e32 v99, v99, v2
	v_add_f32_e32 v100, v103, v100
	v_exp_f32_e32 v99, v99
	v_sub_f32_e32 v101, v108, v2
	v_add_f32_e32 v100, v96, v100
	v_exp_f32_e32 v108, v101
	v_sub_f32_e32 v101, v109, v2
	v_add_f32_e32 v100, v97, v100
	v_exp_f32_e32 v109, v101
	v_sub_f32_e32 v101, v110, v2
	v_add_f32_e32 v100, v98, v100
	v_exp_f32_e32 v110, v101
	v_sub_f32_e32 v101, v111, v2
	v_sub_f32_e32 v88, v88, v3
	v_add_f32_e32 v100, v99, v100
	v_exp_f32_e32 v111, v101
	v_exp_f32_e32 v88, v88
	v_sub_f32_e32 v89, v89, v3
	v_add_f32_e32 v100, v108, v100
	v_exp_f32_e32 v89, v89
	v_sub_f32_e32 v90, v90, v3
	v_add_f32_e32 v100, v109, v100
	v_exp_f32_e32 v90, v90
	v_sub_f32_e32 v91, v91, v3
	v_add_f32_e32 v100, v110, v100
	v_exp_f32_e32 v91, v91
	v_sub_f32_e32 v84, v84, v3
	v_add_f32_e32 v104, v111, v100
	v_cvt_pk_bf16_f32 v100, v149, v105
	v_cvt_pk_bf16_f32 v101, v106, v107
	v_add_f32_e32 v105, 0, v88
	v_exp_f32_e32 v106, v84
	v_sub_f32_e32 v85, v85, v3
	v_add_f32_e32 v105, v89, v105
	v_exp_f32_e32 v107, v85
	v_sub_f32_e32 v85, v86, v3
	v_cvt_pk_bf16_f32 v96, v96, v97
	v_cvt_pk_bf16_f32 v97, v98, v99
	v_cvt_pk_bf16_f32 v98, v108, v109
	v_add_f32_e32 v105, v90, v105
	v_exp_f32_e32 v108, v85
	v_sub_f32_e32 v85, v87, v3
	v_add_f32_e32 v105, v91, v105
	v_exp_f32_e32 v87, v85
	v_sub_f32_e32 v80, v80, v3
	v_add_f32_e32 v84, v106, v105
	v_exp_f32_e32 v80, v80
	v_sub_f32_e32 v81, v81, v3
	v_add_f32_e32 v84, v107, v84
	v_exp_f32_e32 v81, v81
	v_sub_f32_e32 v82, v82, v3
	v_add_f32_e32 v84, v108, v84
	v_exp_f32_e32 v82, v82
	v_sub_f32_e32 v83, v83, v3
	v_add_f32_e32 v84, v87, v84
	v_exp_f32_e32 v83, v83
	v_sub_f32_e32 v85, v92, v3
	v_add_f32_e32 v84, v80, v84
	v_exp_f32_e32 v92, v85
	v_sub_f32_e32 v85, v93, v3
	v_add_f32_e32 v84, v81, v84
	v_exp_f32_e32 v93, v85
	v_sub_f32_e32 v85, v94, v3
	v_add_f32_e32 v84, v82, v84
	v_exp_f32_e32 v94, v85
	v_sub_f32_e32 v85, v95, v3
	v_add_f32_e32 v84, v83, v84
	v_exp_f32_e32 v95, v85
	v_add_f32_e32 v84, v92, v84
	v_add_f32_e32 v84, v93, v84
	v_add_f32_e32 v84, v94, v84
	v_add_f32_e32 v105, v95, v84
	v_fmac_f32_e32 v105, v147, v0
	v_cvt_pk_bf16_f32 v84, v88, v89
	v_cvt_pk_bf16_f32 v85, v90, v91
	v_cvt_pk_bf16_f32 v102, v159, v160
	v_cvt_pk_bf16_f32 v103, v161, v103
	v_cvt_pk_bf16_f32 v86, v106, v107
	v_cvt_pk_bf16_f32 v87, v108, v87
	v_cvt_pk_bf16_f32 v99, v110, v111
	v_cvt_pk_bf16_f32 v80, v80, v81
	v_cvt_pk_bf16_f32 v81, v82, v83
	v_cvt_pk_bf16_f32 v82, v92, v93
	v_cvt_pk_bf16_f32 v83, v94, v95
	v_fmac_f32_e32 v104, v146, v148
	v_mov_b64_e32 v[146:147], v[104:105]
	v_mov_b64_e32 v[148:149], v[2:3]
	s_waitcnt lgkmcnt(0)
	v_mfma_f32_16x16x32_bf16 v[76:79], v[210:213], v[100:103], v[76:79]
	v_mfma_f32_16x16x32_bf16 v[52:55], v[210:213], v[84:87], v[52:55]
	v_mfma_f32_16x16x32_bf16 v[72:75], v[218:221], v[100:103], v[72:75]
	v_mfma_f32_16x16x32_bf16 v[44:47], v[218:221], v[84:87], v[44:47]
	v_mfma_f32_16x16x32_bf16 v[68:71], v[226:229], v[100:103], v[68:71]
	v_mfma_f32_16x16x32_bf16 v[32:35], v[226:229], v[84:87], v[32:35]
	v_mfma_f32_16x16x32_bf16 v[64:67], v[234:237], v[100:103], v[64:67]
	v_mfma_f32_16x16x32_bf16 v[36:39], v[234:237], v[84:87], v[36:39]
	v_mfma_f32_16x16x32_bf16 v[76:79], v[214:217], v[96:99], v[76:79]
	v_mfma_f32_16x16x32_bf16 v[52:55], v[214:217], v[80:83], v[52:55]
	v_mfma_f32_16x16x32_bf16 v[72:75], v[222:225], v[96:99], v[72:75]
	v_mfma_f32_16x16x32_bf16 v[44:47], v[222:225], v[80:83], v[44:47]
	v_mfma_f32_16x16x32_bf16 v[68:71], v[230:233], v[96:99], v[68:71]
	v_mfma_f32_16x16x32_bf16 v[32:35], v[230:233], v[80:83], v[32:35]
	v_mfma_f32_16x16x32_bf16 v[64:67], v[238:241], v[96:99], v[64:67]
	v_mfma_f32_16x16x32_bf16 v[36:39], v[238:241], v[80:83], v[36:39]
.LatA_305:
	s_or_b64 exec, exec, s[14:15]
	s_add_i32 s8, s48, -1
	s_cmp_ge_i32 s8, s78
	s_cbranch_scc1 .LatA_skipst
	s_cmp_ge_i32 s48, s78
	s_cbranch_scc1 .LatA_w0
	s_cmp_eq_u32 s48, 32
	s_cbranch_scc1 .LatA_w0
	s_waitcnt vmcnt(5)
	s_branch .LatA_wd

; DI void attn_item(const int tid_, const Params& p, int l, int item, char* s0, char* s1, char* s2) {
;     ...
;   auto gload = [&](int kt) {
;     int key0, nvalid;
;     tile_info(kt, key0, nvalid);
; #pragma unroll
;     for (int i = 0; i < 3; ++i) {
;       int idx = tid + 256 * i, row = idx / 12, ch = idx - row * 12;
;       const u16* src = (ch < 8) ? KN + (size_t)(key0 + row) * 512 + h * 64 + ch * 8 : KR + (size_t)(key0 + row) * 32 + (ch - 8) * 8;
;       kr[i] = (row < nvalid) ? *(const u32x4*)src : u32x4{0, 0, 0, 0};
;     }
; #pragma unroll
;     for (int i = 0; i < 2; ++i) {
;       int idx = tid + 256 * i, dv = idx >> 3, ch = idx & 7;
;       vr[i] = (ch * 8 < nvalid) ? *(const u32x4*)(VT + (size_t)dv * skv + key0 + ch * 8) : u32x4{0, 0, 0, 0};
;     }
;   };
;   auto lstore = [&](char* buf) {
; #pragma unroll
;     for (int i = 0; i < 3; ++i) {
;       int idx = tid + 256 * i, row = idx / 12, ch = idx - row * 12;
;       *(u32x4*)(buf + row * 208 + ch * 16) = kr[i];
;     }
; #pragma unroll
;     for (int i = 0; i < 2; ++i) {
;       int idx = tid + 256 * i, dv = idx >> 3, ch = idx & 7;
;       *(u32x4*)(buf + 64 * 208 + dv * LDA + ch * 16) = vr[i];
;     }
;   };
;     ...
;     __syncthreads();
.LatA_wd:
	s_and_b64 s[8:9], s[30:31], exec
	s_cselect_b32 s8, 0x6000, 0
	v_add3_u32 v0, s8, v115, v117
	ds_write_b128 v0, v[28:31]
	v_add3_u32 v0, s8, v119, v121
	ds_write_b128 v0, v[40:43]
	v_add3_u32 v0, s8, v152, v153
	s_mov_b32 s8, 0x9400
	s_cselect_b32 s8, s8, 0x3400
	ds_write_b128 v0, v[48:51]
	v_add3_u32 v0, s8, v154, v155
	ds_write_b128 v0, v[56:59]
	v_add3_u32 v0, s8, v156, v155
	ds_write_b128 v0, v[60:63]
.LatA_skipst:
	s_add_i32 s48, s48, 1
	s_add_i32 s49, s49, 64
	s_add_i32 s8, s21, s48
	s_cmp_eq_u32 s8, 2
	s_waitcnt lgkmcnt(0)
	s_barrier
	s_cbranch_scc1 .LBB0_327
	s_branch .LatB_306
.LatB_306:
	s_add_i32 s28, s48, -2
	s_bitcmp0_b32 s28, 0
	s_cselect_b64 s[30:31], -1, 0
	s_cmp_ge_i32 s48, s78
	s_cbranch_scc1 .LatB_319
	s_sub_i32 s50, s49, 48
	s_cmp_eq_u32 s48, 32
	s_cselect_b64 s[8:9], -1, 0
	s_and_b64 s[14:15], s[2:3], s[8:9]
	s_and_b64 s[8:9], s[2:3], exec
	s_cselect_b32 s8, s49, s50
	s_and_b64 s[14:15], s[14:15], exec
	v_mov_b32_e32 v40, v1
	v_mov_b32_e32 v41, v1
	s_cselect_b32 s50, 16, 64
	v_mov_b32_e32 v42, v1
	v_mov_b32_e32 v43, v1
	v_mov_b64_e32 v[28:29], v[40:41]
	v_cmp_gt_i32_e32 vcc, s50, v116
	v_mov_b64_e32 v[30:31], v[42:43]
	s_and_saveexec_b64 s[14:15], vcc
	v_add_u32_e32 v2, s8, v116
	v_ashrrev_i32_e32 v3, 31, v2
	v_lshlrev_b64 v[28:29], 10, v[2:3]
	v_lshlrev_b64 v[2:3], 6, v[2:3]
	v_lshl_add_u64 v[28:29], v[126:127], 0, v[28:29]
	v_lshl_add_u64 v[2:3], v[124:125], 0, v[2:3]
	v_cndmask_b32_e64 v3, v3, v29, s[42:43]
	v_cndmask_b32_e64 v2, v2, v28, s[42:43]
	flat_load_dwordx4 v[28:31], v[2:3]
.LatB_310:
	s_or_b64 exec, exec, s[14:15]
	v_cmp_gt_i32_e32 vcc, s50, v118
	s_and_saveexec_b64 s[14:15], vcc
	v_add_u32_e32 v2, s8, v118
	v_ashrrev_i32_e32 v3, 31, v2
	v_lshlrev_b64 v[40:41], 10, v[2:3]
	v_lshlrev_b64 v[2:3], 6, v[2:3]
	v_lshl_add_u64 v[40:41], v[130:131], 0, v[40:41]
	v_lshl_add_u64 v[2:3], v[128:129], 0, v[2:3]
	v_cndmask_b32_e64 v3, v3, v41, s[44:45]
	v_cndmask_b32_e64 v2, v2, v40, s[44:45]
	flat_load_dwordx4 v[40:43], v[2:3]
.LatB_312:
	s_or_b64 exec, exec, s[14:15]
	v_mov_b32_e32 v2, v1
	v_mov_b32_e32 v3, v1
	v_mov_b32_e32 v0, v1
	v_mov_b64_e32 v[50:51], v[2:3]
	v_cmp_gt_i32_e32 vcc, s50, v120
	v_mov_b64_e32 v[48:49], v[0:1]
	s_and_saveexec_b64 s[14:15], vcc
	v_add_u32_e32 v48, s8, v120
	v_ashrrev_i32_e32 v49, 31, v48
	v_lshlrev_b64 v[50:51], 10, v[48:49]
	v_lshlrev_b64 v[48:49], 6, v[48:49]
	v_lshl_add_u64 v[50:51], v[140:141], 0, v[50:51]
	v_lshl_add_u64 v[48:49], v[138:139], 0, v[48:49]
	v_cndmask_b32_e64 v49, v49, v51, s[46:47]
	v_cndmask_b32_e64 v48, v48, v50, s[46:47]
	flat_load_dwordx4 v[48:51], v[48:49]
.LatB_314:
	s_or_b64 exec, exec, s[14:15]
	v_mov_b64_e32 v[58:59], v[2:3]
	s_ashr_i32 s9, s8, 31
	v_cmp_gt_u32_e32 vcc, s50, v122
	v_mov_b64_e32 v[56:57], v[0:1]
	s_and_saveexec_b64 s[14:15], vcc
	v_lshl_add_u64 v[2:3], s[8:9], 1, v[142:143]
	flat_load_dwordx4 v[56:59], v[2:3]
.LatB_316:
	s_or_b64 exec, exec, s[14:15]
	v_mov_b32_e32 v2, v1
	v_mov_b32_e32 v3, v1
	v_mov_b32_e32 v0, v1
	v_mov_b64_e32 v[62:63], v[2:3]
	v_mov_b64_e32 v[60:61], v[0:1]
	s_and_saveexec_b64 s[14:15], vcc
	v_lshl_add_u64 v[2:3], s[8:9], 1, v[144:145]
	flat_load_dwordx4 v[60:63], v[2:3]

; DI u32x2 pack4(f32x4 v) { return u32x2{pack2(v[0], v[1]), pack2(v[2], v[3])}; }
; DI float xmax16(float x) { u32x2 r = __builtin_amdgcn_permlane16_swap(__float_as_uint(x), __float_as_uint(x), false, false); return fmaxf(__uint_as_float(r.x), __uint_as_float(r.y)); }
; DI float xmax32(float x) { u32x2 r = __builtin_amdgcn_permlane32_swap(__float_as_uint(x), __float_as_uint(x), false, false); return fmaxf(__uint_as_float(r.x), __uint_as_float(r.y)); }
; DI void attn_item(const int tid_, const Params& p, int l, int item, char* s0, char* s1, char* s2) {
;     ...
;       bf16x8 pf[2][2];
; #pragma unroll
;       for (int nt = 0; nt < 2; ++nt) {
;         float mx = -1e30f;
; #pragma unroll
;         for (int mt = 0; mt < 4; ++mt)
; #pragma unroll
;           for (int e = 0; e < 4; ++e) mx = fmaxf(mx, s[mt][nt][e]);
;         mx = xmax16(mx);
;         mx = xmax32(mx);
;         const float mnew = fmaxf(mrow[nt], mx);
;         const float alpha = __builtin_amdgcn_exp2f(mrow[nt] - mnew);
;         mrow[nt] = mnew;
;         float ps = 0.f;
; #pragma unroll
;         for (int mt = 0; mt < 4; ++mt)
; #pragma unroll
;           for (int e = 0; e < 4; ++e) {
;             float pv = __builtin_amdgcn_exp2f(s[mt][nt][e] - mnew);
;             s[mt][nt][e] = pv;
;             ps += pv;
;           }
;         lsum[nt] = lsum[nt] * alpha + ps;
;         if (__builtin_amdgcn_ballot_w64(alpha != 1.f) != 0ull) {
; #pragma unroll
;           for (int dt = 0; dt < 4; ++dt) o[dt][nt] *= alpha;
;         }
; #pragma unroll
;         for (int kk = 0; kk < 2; ++kk) {
;           u32x2 lo = pack4(s[2 * kk][nt]), hi = pack4(s[2 * kk + 1][nt]);
;           u32x4 pk = u32x4{lo.x, lo.y, hi.x, hi.y};
;           pf[nt][kk] = __builtin_bit_cast(bf16x8, pk);
;         }
;       }
;       const char* sV = cur + 64 * 208;
; #pragma unroll
;       for (int dt = 0; dt < 4; ++dt)
; #pragma unroll
;         for (int kk = 0; kk < 2; ++kk) {
;           u32x2 lo = *(const u32x2*)(sV + (dt * 16 + c16) * LDA + (kk * 32 + g * 4) * 2);
;           u32x2 hi = *(const u32x2*)(sV + (dt * 16 + c16) * LDA + (kk * 32 + 16 + g * 4) * 2);
;           u32x4 pk = u32x4{lo.x, lo.y, hi.x, hi.y};
;           bf16x8 vf = __builtin_bit_cast(bf16x8, pk);
; #pragma unroll
;           for (int nt = 0; nt < 2; ++nt) o[dt][nt] = __builtin_amdgcn_mfma_f32_16x16x32_bf16(vf, pf[nt][kk], o[dt][nt], 0, 0, 0);
;         }
.LatB_324:
	v_max3_f32 v0, v88, s8, v89
	v_max3_f32 v0, v0, v90, v91
	v_max3_f32 v0, v0, v84, v85
	v_max3_f32 v0, v0, v86, v87
	v_max3_f32 v0, v0, v80, v81
	v_max3_f32 v0, v0, v82, v83
	v_max3_f32 v0, v0, v92, v93
	v_max3_f32 v0, v0, v94, v95
	v_mov_b32_e32 v3, v0
	s_nop 1
	v_permlane16_swap_b32_e32 v0, v3
	v_max_f32_e32 v3, v3, v3
	v_max_f32_e32 v0, v0, v0
	v_max_f32_e32 v0, v0, v3
	v_mov_b32_e32 v3, v0
	s_nop 1
	v_permlane32_swap_b32_e32 v0, v3
	v_max3_f32 v3, v149, v0, v3
	v_sub_f32_e32 v0, v149, v3
	v_exp_f32_e32 v0, v0
	s_nop 0
	v_cmp_neq_f32_e32 vcc, 1.0, v0
	s_cbranch_vccz .LatB_304
	v_pk_mul_f32 v[54:55], v[54:55], v[0:1] op_sel_hi:[1,0]
	v_pk_mul_f32 v[52:53], v[52:53], v[0:1] op_sel_hi:[1,0]
	v_pk_mul_f32 v[46:47], v[46:47], v[0:1] op_sel_hi:[1,0]
	v_pk_mul_f32 v[44:45], v[44:45], v[0:1] op_sel_hi:[1,0]
	v_pk_mul_f32 v[34:35], v[34:35], v[0:1] op_sel_hi:[1,0]
	v_pk_mul_f32 v[32:33], v[32:33], v[0:1] op_sel_hi:[1,0]
	v_pk_mul_f32 v[38:39], v[38:39], v[0:1] op_sel_hi:[1,0]
	v_pk_mul_f32 v[36:37], v[36:37], v[0:1] op_sel_hi:[1,0]
	s_branch .LatB_304
.LatB_304:
	v_sub_f32_e32 v104, v104, v2
	v_exp_f32_e32 v149, v104
	v_sub_f32_e32 v105, v105, v2
	v_exp_f32_e32 v105, v105
	v_sub_f32_e32 v106, v106, v2
	v_exp_f32_e32 v106, v106
	v_sub_f32_e32 v107, v107, v2
	v_exp_f32_e32 v107, v107
	v_sub_f32_e32 v100, v100, v2
	v_add_f32_e32 v104, 0, v149
	v_exp_f32_e32 v159, v100
	v_sub_f32_e32 v101, v101, v2
	v_add_f32_e32 v104, v105, v104
	v_exp_f32_e32 v160, v101
	v_sub_f32_e32 v101, v102, v2
	v_add_f32_e32 v104, v106, v104
	v_exp_f32_e32 v161, v101
	v_sub_f32_e32 v101, v103, v2
	v_add_f32_e32 v104, v107, v104
	v_exp_f32_e32 v103, v101
	v_sub_f32_e32 v96, v96, v2
	v_add_f32_e32 v100, v159, v104
	v_exp_f32_e32 v96, v96
	v_sub_f32_e32 v97, v97, v2
	v_add_f32_e32 v100, v160, v100
	v_exp_f32_e32 v97, v97
	v_sub_f32_e32 v98, v98, v2
	v_add_f32_e32 v100, v161, v100
	v_exp_f32_e32 v98, v98
	v_sub_f32_e32 v99, v99, v2
	v_add_f32_e32 v100, v103, v100
	v_exp_f32_e32 v99, v99
	v_sub_f32_e32 v101, v108, v2
	v_add_f32_e32 v100, v96, v100
	v_exp_f32_e32 v108, v101
	v_sub_f32_e32 v101, v109, v2
	v_add_f32_e32 v100, v97, v100
	v_exp_f32_e32 v109, v101
	v_sub_f32_e32 v101, v110, v2
	v_add_f32_e32 v100, v98, v100
	v_exp_f32_e32 v110, v101
	v_sub_f32_e32 v101, v111, v2
	v_sub_f32_e32 v88, v88, v3
	v_add_f32_e32 v100, v99, v100
	v_exp_f32_e32 v111, v101
	v_exp_f32_e32 v88, v88
	v_sub_f32_e32 v89, v89, v3
	v_add_f32_e32 v100, v108, v100
	v_exp_f32_e32 v89, v89
	v_sub_f32_e32 v90, v90, v3
	v_add_f32_e32 v100, v109, v100
	v_exp_f32_e32 v90, v90
	v_sub_f32_e32 v91, v91, v3
	v_add_f32_e32 v100, v110, v100
	v_exp_f32_e32 v91, v91
	v_sub_f32_e32 v84, v84, v3
	v_add_f32_e32 v104, v111, v100
	v_cvt_pk_bf16_f32 v100, v149, v105
	v_cvt_pk_bf16_f32 v101, v106, v107
	v_add_f32_e32 v105, 0, v88
	v_exp_f32_e32 v106, v84
	v_sub_f32_e32 v85, v85, v3
	v_add_f32_e32 v105, v89, v105
	v_exp_f32_e32 v107, v85
	v_sub_f32_e32 v85, v86, v3
	v_cvt_pk_bf16_f32 v96, v96, v97
	v_cvt_pk_bf16_f32 v97, v98, v99
	v_cvt_pk_bf16_f32 v98, v108, v109
	v_add_f32_e32 v105, v90, v105
	v_exp_f32_e32 v108, v85
	v_sub_f32_e32 v85, v87, v3
	v_add_f32_e32 v105, v91, v105
	v_exp_f32_e32 v87, v85
	v_sub_f32_e32 v80, v80, v3
	v_add_f32_e32 v84, v106, v105
	v_exp_f32_e32 v80, v80
	v_sub_f32_e32 v81, v81, v3
	v_add_f32_e32 v84, v107, v84
	v_exp_f32_e32 v81, v81
	v_sub_f32_e32 v82, v82, v3
	v_add_f32_e32 v84, v108, v84
	v_exp_f32_e32 v82, v82
	v_sub_f32_e32 v83, v83, v3
	v_add_f32_e32 v84, v87, v84
	v_exp_f32_e32 v83, v83
	v_sub_f32_e32 v85, v92, v3
	v_add_f32_e32 v84, v80, v84
	v_exp_f32_e32 v92, v85
	v_sub_f32_e32 v85, v93, v3
	v_add_f32_e32 v84, v81, v84
	v_exp_f32_e32 v93, v85
	v_sub_f32_e32 v85, v94, v3
	v_add_f32_e32 v84, v82, v84
	v_exp_f32_e32 v94, v85
	v_sub_f32_e32 v85, v95, v3
	v_add_f32_e32 v84, v83, v84
	v_exp_f32_e32 v95, v85
	v_add_f32_e32 v84, v92, v84
	v_add_f32_e32 v84, v93, v84
	v_add_f32_e32 v84, v94, v84
	v_add_f32_e32 v105, v95, v84
	v_fmac_f32_e32 v105, v147, v0
	v_cvt_pk_bf16_f32 v84, v88, v89
	v_cvt_pk_bf16_f32 v85, v90, v91
	v_cvt_pk_bf16_f32 v102, v159, v160
	v_cvt_pk_bf16_f32 v103, v161, v103
	v_cvt_pk_bf16_f32 v86, v106, v107
	v_cvt_pk_bf16_f32 v87, v108, v87
	v_cvt_pk_bf16_f32 v99, v110, v111
	v_cvt_pk_bf16_f32 v80, v80, v81
	v_cvt_pk_bf16_f32 v81, v82, v83
	v_cvt_pk_bf16_f32 v82, v92, v93
	v_cvt_pk_bf16_f32 v83, v94, v95
	v_fmac_f32_e32 v104, v146, v148
	v_mov_b64_e32 v[146:147], v[104:105]
	v_mov_b64_e32 v[148:149], v[2:3]
	s_waitcnt lgkmcnt(0)
	v_mfma_f32_16x16x32_bf16 v[76:79], v[210:213], v[100:103], v[76:79]
	v_mfma_f32_16x16x32_bf16 v[52:55], v[210:213], v[84:87], v[52:55]
	v_mfma_f32_16x16x32_bf16 v[72:75], v[218:221], v[100:103], v[72:75]
	v_mfma_f32_16x16x32_bf16 v[44:47], v[218:221], v[84:87], v[44:47]
	v_mfma_f32_16x16x32_bf16 v[68:71], v[226:229], v[100:103], v[68:71]
	v_mfma_f32_16x16x32_bf16 v[32:35], v[226:229], v[84:87], v[32:35]
	v_mfma_f32_16x16x32_bf16 v[64:67], v[234:237], v[100:103], v[64:67]
	v_mfma_f32_16x16x32_bf16 v[36:39], v[234:237], v[84:87], v[36:39]
	v_mfma_f32_16x16x32_bf16 v[76:79], v[214:217], v[96:99], v[76:79]
	v_mfma_f32_16x16x32_bf16 v[52:55], v[214:217], v[80:83], v[52:55]
	v_mfma_f32_16x16x32_bf16 v[72:75], v[222:225], v[96:99], v[72:75]
	v_mfma_f32_16x16x32_bf16 v[44:47], v[222:225], v[80:83], v[44:47]
	v_mfma_f32_16x16x32_bf16 v[68:71], v[230:233], v[96:99], v[68:71]
	v_mfma_f32_16x16x32_bf16 v[32:35], v[230:233], v[80:83], v[32:35]
	v_mfma_f32_16x16x32_bf16 v[64:67], v[238:241], v[96:99], v[64:67]
	v_mfma_f32_16x16x32_bf16 v[36:39], v[238:241], v[80:83], v[36:39]

; DI void attn_item(const int tid_, const Params& p, int l, int item, char* s0, char* s1, char* s2) {
;     ...
;   auto lstore = [&](char* buf) {
; #pragma unroll
;     for (int i = 0; i < 3; ++i) {
;       int idx = tid + 256 * i, row = idx / 12, ch = idx - row * 12;
;       *(u32x4*)(buf + row * 208 + ch * 16) = kr[i];
;     }
; #pragma unroll
;     for (int i = 0; i < 2; ++i) {
;       int idx = tid + 256 * i, dv = idx >> 3, ch = idx & 7;
;       *(u32x4*)(buf + 64 * 208 + dv * LDA + ch * 16) = vr[i];
;     }
;   };
.LatB_wd:
	s_and_b64 s[8:9], s[30:31], exec
	s_cselect_b32 s8, 0x6000, 0
	v_add3_u32 v0, s8, v115, v117
	ds_write_b128 v0, v[190:193]
	v_add3_u32 v0, s8, v119, v121
	ds_write_b128 v0, v[194:197]
	v_add3_u32 v0, s8, v152, v153
	s_mov_b32 s8, 0x9400
	s_cselect_b32 s8, s8, 0x3400
	ds_write_b128 v0, v[198:201]
	v_add3_u32 v0, s8, v154, v155
	ds_write_b128 v0, v[206:209]
	v_add3_u32 v0, s8, v156, v155
	ds_write_b128 v0, v[172:175]
